# SwiGLU GEMM epilogues (both FFNs) rewritten with packed f32 mul/add, interleaved chains, no trans-hazard nops
# speedup vs baseline: 1.0007x; 1.0007x over previous
.LBB0_80:
	v_readfirstlane_b32 s1, v15
	v_readfirstlane_b32 s0, v14
	s_nop 1
	v_lshl_add_u64 v[24:25], s[0:1], 0, v[10:11]
	v_lshl_add_u64 v[24:25], v[24:25], 0, s[12:13]
	v_add_co_u32_e64 v28, s[0:1], s14, v24
	flat_load_dwordx2 v[32:33], v[24:25]
	s_nop 0
	v_addc_co_u32_e64 v29, s[0:1], 0, v25, s[0:1]
	flat_load_dwordx2 v[34:35], v[28:29]
	flat_load_dwordx4 v[24:27], v[16:17]
	v_add_co_u32_e64 v28, s[0:1], s9, v16
	s_add_u32 s12, s12, 8
	s_nop 0
	v_addc_co_u32_e64 v29, s[0:1], 0, v17, s[0:1]
	flat_load_dwordx4 v[28:31], v[28:29]
	s_addc_u32 s13, s13, 0
	v_lshl_add_u64 v[16:17], v[16:17], 0, s[10:11]
	s_cmpk_eq_i32 s12, 0x100
	s_waitcnt vmcnt(0) lgkmcnt(0)
	v_mul_f32_e32 v36, 0xbfb8aa3b, v32
	v_mul_f32_e32 v37, 0xbfb8aa3b, v33
	v_mul_f32_e32 v38, 0xbfb8aa3b, v34
	v_exp_f32_e32 v36, v36
	v_mul_f32_e32 v39, 0xbfb8aa3b, v35
	v_exp_f32_e32 v38, v38
	v_exp_f32_e32 v37, v37
	v_exp_f32_e32 v39, v39
	v_add_f32_e32 v36, 1.0, v36
	v_add_f32_e32 v38, 1.0, v38
	v_add_f32_e32 v37, 1.0, v37
	v_rcp_f32_e32 v36, v36
	v_add_f32_e32 v39, 1.0, v39
	v_rcp_f32_e32 v38, v38
	v_rcp_f32_e32 v37, v37
	v_rcp_f32_e32 v39, v39
	v_mul_f32_e32 v32, v32, v36
	v_mul_f32_e32 v34, v34, v38
	v_mul_f32_e32 v36, v33, v37
	v_pk_fma_f32 v[6:7], v[26:27], v[32:33], v[6:7] op_sel_hi:[1,0,1]
	v_pk_fma_f32 v[4:5], v[24:25], v[32:33], v[4:5] op_sel_hi:[1,0,1]
	v_mul_f32_e32 v32, v35, v39
	v_pk_fma_f32 v[0:1], v[24:25], v[34:35], v[0:1] op_sel_hi:[1,0,1]
	v_pk_fma_f32 v[2:3], v[26:27], v[34:35], v[2:3] op_sel_hi:[1,0,1]
	v_pk_fma_f32 v[4:5], v[28:29], v[36:37], v[4:5] op_sel_hi:[1,0,1]
	v_pk_fma_f32 v[6:7], v[30:31], v[36:37], v[6:7] op_sel_hi:[1,0,1]
	v_pk_fma_f32 v[2:3], v[30:31], v[32:33], v[2:3] op_sel_hi:[1,0,1]
	v_pk_fma_f32 v[0:1], v[28:29], v[32:33], v[0:1] op_sel_hi:[1,0,1]
	s_cbranch_scc0 .LBB0_80
	ds_write_b128 v23, v[4:7]
	ds_write_b128 v23, v[0:3] offset:16
	s_waitcnt lgkmcnt(0)
	s_barrier
	s_and_saveexec_b64 s[0:1], vcc
	s_cbranch_execz .LBB0_78
	v_mov_b32_e32 v0, s15
	ds_read_b64 v[0:1], v0
	v_or_b32_e32 v2, s18, v19
	s_mul_i32 s19, s17, 0x12000
	s_mul_hi_i32 s13, s17, 0x12000
	v_ashrrev_i32_e32 v3, 31, v2
	s_waitcnt lgkmcnt(0)
	v_readfirstlane_b32 s12, v0
	v_readfirstlane_b32 s18, v1
	s_add_u32 s12, s12, s19
	s_addc_u32 s13, s18, s13
	v_lshlrev_b64 v[0:1], 2, v[2:3]
	v_lshl_add_u64 v[2:3], s[12:13], 0, v[0:1]
	flat_load_dword v48, v[2:3]
	ds_read2st64_b32 v[2:3], v18 offset1:2
	ds_read2st64_b32 v[4:5], v18 offset0:4 offset1:6
	ds_read2st64_b32 v[6:7], v18 offset0:8 offset1:10
	ds_read2st64_b32 v[14:15], v18 offset0:12 offset1:14
	ds_read2st64_b32 v[16:17], v18 offset0:16 offset1:18
	ds_read2st64_b32 v[24:25], v18 offset0:20 offset1:22
	ds_read2st64_b32 v[26:27], v18 offset0:24 offset1:26
	ds_read2st64_b32 v[28:29], v18 offset0:28 offset1:30
	ds_read2st64_b32 v[30:31], v18 offset0:32 offset1:34
	ds_read2st64_b32 v[32:33], v18 offset0:36 offset1:38
	ds_read2st64_b32 v[34:35], v18 offset0:40 offset1:42
	ds_read2st64_b32 v[36:37], v18 offset0:44 offset1:46
	ds_read2st64_b32 v[38:39], v18 offset0:48 offset1:50
	ds_read2st64_b32 v[40:41], v18 offset0:52 offset1:54
	ds_read2st64_b32 v[42:43], v18 offset0:56 offset1:58
	ds_read2st64_b32 v[44:45], v18 offset0:60 offset1:62
	s_waitcnt lgkmcnt(0)
	v_add_f32_e32 v2, 0, v2
	v_add_f32_e32 v2, v2, v3
	v_add_f32_e32 v2, v2, v4
	v_add_f32_e32 v2, v2, v5
	v_add_f32_e32 v2, v2, v6
	v_add_f32_e32 v2, v2, v7
	v_add_f32_e32 v2, v2, v14
	v_add_f32_e32 v2, v2, v15
	v_add_f32_e32 v2, v2, v16
	v_add_f32_e32 v2, v2, v17
	v_add_f32_e32 v2, v2, v24
	v_add_f32_e32 v2, v2, v25
	v_add_f32_e32 v2, v2, v26
	v_add_f32_e32 v2, v2, v27
	v_add_f32_e32 v2, v2, v28
	v_add_f32_e32 v2, v2, v29
	v_add_f32_e32 v2, v2, v30
	v_add_f32_e32 v2, v2, v31
	v_add_f32_e32 v2, v2, v32
	v_add_f32_e32 v2, v2, v33
	v_add_f32_e32 v2, v2, v34
	v_add_f32_e32 v2, v2, v35
	v_add_f32_e32 v2, v2, v36
	v_add_f32_e32 v2, v2, v37
	v_add_f32_e32 v2, v2, v38
	v_add_f32_e32 v2, v2, v39
	v_add_f32_e32 v2, v2, v40
	v_add_f32_e32 v2, v2, v41
	v_add_f32_e32 v2, v2, v42
	v_add_f32_e32 v2, v2, v43
	v_lshl_add_u32 v49, s17, 1, v8
	v_mov_b64_e32 v[46:47], s[4:5]
	v_add_f32_e32 v2, v2, v44
	v_mad_i64_i32 v[46:47], s[12:13], v49, s9, v[46:47]
	v_add_f32_e32 v2, v2, v45
	v_lshl_add_u64 v[0:1], v[46:47], 0, v[0:1]
	s_waitcnt vmcnt(0)
	v_add_f32_e32 v2, v2, v48
	flat_store_dword v[0:1], v2
	s_branch .LBB0_78

.LBB0_222:
	v_lshl_or_b32 v144, s60, 7, v147
	v_lshl_add_u32 v149, s40, 8, v17
	s_mov_b32 s100, 0xbfb8aa3b
	s_mov_b32 s101, 0xbfb8aa3b
	v_ashrrev_i32_e32 v145, 31, v144
	v_mov_b64_e32 v[142:143], s[12:13]
	s_movk_i32 s23, 0x2c00
	v_mov_b32_e32 v250, 1.0
	v_mov_b32_e32 v251, 1.0
	v_lshlrev_b64 v[144:145], 1, v[144:145]
	v_mad_i64_i32 v[176:177], s[4:5], v149, s23, v[142:143]
	v_pk_mul_f32 v[160:161], v[126:127], s[100:101]
	v_pk_mul_f32 v[162:163], v[128:129], s[100:101]
	v_pk_mul_f32 v[164:165], v[118:119], s[100:101]
	v_pk_mul_f32 v[166:167], v[120:121], s[100:101]
	v_lshl_add_u64 v[176:177], v[176:177], 0, v[144:145]
	v_exp_f32_e32 v160, v160
	v_exp_f32_e32 v161, v161
	v_exp_f32_e32 v162, v162
	v_exp_f32_e32 v163, v163
	v_exp_f32_e32 v164, v164
	v_exp_f32_e32 v165, v165
	v_exp_f32_e32 v166, v166
	v_exp_f32_e32 v167, v167
	v_pk_mul_f32 v[126:127], v[126:127], v[122:123]
	v_pk_mul_f32 v[128:129], v[128:129], v[124:125]
	v_pk_mul_f32 v[118:119], v[118:119], v[114:115]
	v_pk_mul_f32 v[120:121], v[120:121], v[116:117]
	v_pk_add_f32 v[160:161], v[160:161], v[250:251]
	v_pk_add_f32 v[162:163], v[162:163], v[250:251]
	v_pk_add_f32 v[164:165], v[164:165], v[250:251]
	v_pk_add_f32 v[166:167], v[166:167], v[250:251]
	v_rcp_f32_e32 v160, v160
	v_rcp_f32_e32 v161, v161
	v_rcp_f32_e32 v162, v162
	v_rcp_f32_e32 v163, v163
	v_rcp_f32_e32 v164, v164
	v_rcp_f32_e32 v165, v165
	v_rcp_f32_e32 v166, v166
	v_rcp_f32_e32 v167, v167
	v_pk_mul_f32 v[126:127], v[160:161], v[126:127]
	v_pk_mul_f32 v[128:129], v[162:163], v[128:129]
	v_pk_mul_f32 v[118:119], v[164:165], v[118:119]
	v_pk_mul_f32 v[120:121], v[166:167], v[120:121]
	v_cvt_pk_bf16_f32 v168, v126, v127
	v_cvt_pk_bf16_f32 v169, v128, v129
	v_cvt_pk_bf16_f32 v170, v118, v119
	v_cvt_pk_bf16_f32 v171, v120, v121
	flat_store_dwordx4 v[176:177], v[168:171]
	v_add_u32_e32 v178, 0x10, v149
	v_mad_i64_i32 v[178:179], s[4:5], v178, s23, v[142:143]
	v_pk_mul_f32 v[160:161], v[110:111], s[100:101]
	v_pk_mul_f32 v[162:163], v[112:113], s[100:101]
	v_pk_mul_f32 v[164:165], v[102:103], s[100:101]
	v_pk_mul_f32 v[166:167], v[104:105], s[100:101]
	v_lshl_add_u64 v[178:179], v[178:179], 0, v[144:145]
	v_exp_f32_e32 v160, v160
	v_exp_f32_e32 v161, v161
	v_exp_f32_e32 v162, v162
	v_exp_f32_e32 v163, v163
	v_exp_f32_e32 v164, v164
	v_exp_f32_e32 v165, v165
	v_exp_f32_e32 v166, v166
	v_exp_f32_e32 v167, v167
	v_pk_mul_f32 v[110:111], v[110:111], v[106:107]
	v_pk_mul_f32 v[112:113], v[112:113], v[108:109]
	v_pk_mul_f32 v[102:103], v[102:103], v[98:99]
	v_pk_mul_f32 v[104:105], v[104:105], v[100:101]
	v_pk_add_f32 v[160:161], v[160:161], v[250:251]
	v_pk_add_f32 v[162:163], v[162:163], v[250:251]
	v_pk_add_f32 v[164:165], v[164:165], v[250:251]
	v_pk_add_f32 v[166:167], v[166:167], v[250:251]
	v_rcp_f32_e32 v160, v160
	v_rcp_f32_e32 v161, v161
	v_rcp_f32_e32 v162, v162
	v_rcp_f32_e32 v163, v163
	v_rcp_f32_e32 v164, v164
	v_rcp_f32_e32 v165, v165
	v_rcp_f32_e32 v166, v166
	v_rcp_f32_e32 v167, v167
	v_pk_mul_f32 v[110:111], v[160:161], v[110:111]
	v_pk_mul_f32 v[112:113], v[162:163], v[112:113]
	v_pk_mul_f32 v[102:103], v[164:165], v[102:103]
	v_pk_mul_f32 v[104:105], v[166:167], v[104:105]
	v_cvt_pk_bf16_f32 v172, v110, v111
	v_cvt_pk_bf16_f32 v173, v112, v113
	v_cvt_pk_bf16_f32 v174, v102, v103
	v_cvt_pk_bf16_f32 v175, v104, v105
	flat_store_dwordx4 v[178:179], v[172:175]
	v_add_u32_e32 v176, 0x20, v149
	v_mad_i64_i32 v[176:177], s[4:5], v176, s23, v[142:143]
	v_pk_mul_f32 v[160:161], v[94:95], s[100:101]
	v_pk_mul_f32 v[162:163], v[96:97], s[100:101]
	v_pk_mul_f32 v[164:165], v[86:87], s[100:101]
	v_pk_mul_f32 v[166:167], v[88:89], s[100:101]
	v_lshl_add_u64 v[176:177], v[176:177], 0, v[144:145]
	v_exp_f32_e32 v160, v160
	v_exp_f32_e32 v161, v161
	v_exp_f32_e32 v162, v162
	v_exp_f32_e32 v163, v163
	v_exp_f32_e32 v164, v164
	v_exp_f32_e32 v165, v165
	v_exp_f32_e32 v166, v166
	v_exp_f32_e32 v167, v167
	v_pk_mul_f32 v[94:95], v[94:95], v[90:91]
	v_pk_mul_f32 v[96:97], v[96:97], v[92:93]
	v_pk_mul_f32 v[86:87], v[86:87], v[82:83]
	v_pk_mul_f32 v[88:89], v[88:89], v[84:85]
	v_pk_add_f32 v[160:161], v[160:161], v[250:251]
	v_pk_add_f32 v[162:163], v[162:163], v[250:251]
	v_pk_add_f32 v[164:165], v[164:165], v[250:251]
	v_pk_add_f32 v[166:167], v[166:167], v[250:251]
	v_rcp_f32_e32 v160, v160
	v_rcp_f32_e32 v161, v161
	v_rcp_f32_e32 v162, v162
	v_rcp_f32_e32 v163, v163
	v_rcp_f32_e32 v164, v164
	v_rcp_f32_e32 v165, v165
	v_rcp_f32_e32 v166, v166
	v_rcp_f32_e32 v167, v167
	v_pk_mul_f32 v[94:95], v[160:161], v[94:95]
	v_pk_mul_f32 v[96:97], v[162:163], v[96:97]
	v_pk_mul_f32 v[86:87], v[164:165], v[86:87]
	v_pk_mul_f32 v[88:89], v[166:167], v[88:89]
	v_cvt_pk_bf16_f32 v168, v94, v95
	v_cvt_pk_bf16_f32 v169, v96, v97
	v_cvt_pk_bf16_f32 v170, v86, v87
	v_cvt_pk_bf16_f32 v171, v88, v89
	flat_store_dwordx4 v[176:177], v[168:171]
	v_add_u32_e32 v178, 0x30, v149
	v_mad_i64_i32 v[178:179], s[4:5], v178, s23, v[142:143]
	v_pk_mul_f32 v[160:161], v[78:79], s[100:101]
	v_pk_mul_f32 v[162:163], v[80:81], s[100:101]
	v_pk_mul_f32 v[164:165], v[70:71], s[100:101]
	v_pk_mul_f32 v[166:167], v[72:73], s[100:101]
	v_lshl_add_u64 v[178:179], v[178:179], 0, v[144:145]
	v_exp_f32_e32 v160, v160
	v_exp_f32_e32 v161, v161
	v_exp_f32_e32 v162, v162
	v_exp_f32_e32 v163, v163
	v_exp_f32_e32 v164, v164
	v_exp_f32_e32 v165, v165
	v_exp_f32_e32 v166, v166
	v_exp_f32_e32 v167, v167
	v_pk_mul_f32 v[78:79], v[78:79], v[74:75]
	v_pk_mul_f32 v[80:81], v[80:81], v[76:77]
	v_pk_mul_f32 v[70:71], v[70:71], v[66:67]
	v_pk_mul_f32 v[72:73], v[72:73], v[68:69]
	v_pk_add_f32 v[160:161], v[160:161], v[250:251]
	v_pk_add_f32 v[162:163], v[162:163], v[250:251]
	v_pk_add_f32 v[164:165], v[164:165], v[250:251]
	v_pk_add_f32 v[166:167], v[166:167], v[250:251]
	v_rcp_f32_e32 v160, v160
	v_rcp_f32_e32 v161, v161
	v_rcp_f32_e32 v162, v162
	v_rcp_f32_e32 v163, v163
	v_rcp_f32_e32 v164, v164
	v_rcp_f32_e32 v165, v165
	v_rcp_f32_e32 v166, v166
	v_rcp_f32_e32 v167, v167
	v_pk_mul_f32 v[78:79], v[160:161], v[78:79]
	v_pk_mul_f32 v[80:81], v[162:163], v[80:81]
	v_pk_mul_f32 v[70:71], v[164:165], v[70:71]
	v_pk_mul_f32 v[72:73], v[166:167], v[72:73]
	v_cvt_pk_bf16_f32 v172, v78, v79
	v_cvt_pk_bf16_f32 v173, v80, v81
	v_cvt_pk_bf16_f32 v174, v70, v71
	v_cvt_pk_bf16_f32 v175, v72, v73
	flat_store_dwordx4 v[178:179], v[172:175]
	v_add_u32_e32 v176, 0x80, v149
	v_mad_i64_i32 v[176:177], s[4:5], v176, s23, v[142:143]
	v_pk_mul_f32 v[160:161], v[62:63], s[100:101]
	v_pk_mul_f32 v[162:163], v[64:65], s[100:101]
	v_pk_mul_f32 v[164:165], v[54:55], s[100:101]
	v_pk_mul_f32 v[166:167], v[56:57], s[100:101]
	v_lshl_add_u64 v[176:177], v[176:177], 0, v[144:145]
	v_exp_f32_e32 v160, v160
	v_exp_f32_e32 v161, v161
	v_exp_f32_e32 v162, v162
	v_exp_f32_e32 v163, v163
	v_exp_f32_e32 v164, v164
	v_exp_f32_e32 v165, v165
	v_exp_f32_e32 v166, v166
	v_exp_f32_e32 v167, v167
	v_pk_mul_f32 v[62:63], v[62:63], v[58:59]
	v_pk_mul_f32 v[64:65], v[64:65], v[60:61]
	v_pk_mul_f32 v[54:55], v[54:55], v[50:51]
	v_pk_mul_f32 v[56:57], v[56:57], v[52:53]
	v_pk_add_f32 v[160:161], v[160:161], v[250:251]
	v_pk_add_f32 v[162:163], v[162:163], v[250:251]
	v_pk_add_f32 v[164:165], v[164:165], v[250:251]
	v_pk_add_f32 v[166:167], v[166:167], v[250:251]
	v_rcp_f32_e32 v160, v160
	v_rcp_f32_e32 v161, v161
	v_rcp_f32_e32 v162, v162
	v_rcp_f32_e32 v163, v163
	v_rcp_f32_e32 v164, v164
	v_rcp_f32_e32 v165, v165
	v_rcp_f32_e32 v166, v166
	v_rcp_f32_e32 v167, v167
	v_pk_mul_f32 v[62:63], v[160:161], v[62:63]
	v_pk_mul_f32 v[64:65], v[162:163], v[64:65]
	v_pk_mul_f32 v[54:55], v[164:165], v[54:55]
	v_pk_mul_f32 v[56:57], v[166:167], v[56:57]
	v_cvt_pk_bf16_f32 v168, v62, v63
	v_cvt_pk_bf16_f32 v169, v64, v65
	v_cvt_pk_bf16_f32 v170, v54, v55
	v_cvt_pk_bf16_f32 v171, v56, v57
	flat_store_dwordx4 v[176:177], v[168:171]
	v_add_u32_e32 v178, 0x90, v149
	v_mad_i64_i32 v[178:179], s[4:5], v178, s23, v[142:143]
	v_pk_mul_f32 v[160:161], v[46:47], s[100:101]
	v_pk_mul_f32 v[162:163], v[48:49], s[100:101]
	v_pk_mul_f32 v[164:165], v[38:39], s[100:101]
	v_pk_mul_f32 v[166:167], v[40:41], s[100:101]
	v_lshl_add_u64 v[178:179], v[178:179], 0, v[144:145]
	v_exp_f32_e32 v160, v160
	v_exp_f32_e32 v161, v161
	v_exp_f32_e32 v162, v162
	v_exp_f32_e32 v163, v163
	v_exp_f32_e32 v164, v164
	v_exp_f32_e32 v165, v165
	v_exp_f32_e32 v166, v166
	v_exp_f32_e32 v167, v167
	v_pk_mul_f32 v[46:47], v[46:47], v[42:43]
	v_pk_mul_f32 v[48:49], v[48:49], v[44:45]
	v_pk_mul_f32 v[38:39], v[38:39], v[34:35]
	v_pk_mul_f32 v[40:41], v[40:41], v[36:37]
	v_pk_add_f32 v[160:161], v[160:161], v[250:251]
	v_pk_add_f32 v[162:163], v[162:163], v[250:251]
	v_pk_add_f32 v[164:165], v[164:165], v[250:251]
	v_pk_add_f32 v[166:167], v[166:167], v[250:251]
	v_rcp_f32_e32 v160, v160
	v_rcp_f32_e32 v161, v161
	v_rcp_f32_e32 v162, v162
	v_rcp_f32_e32 v163, v163
	v_rcp_f32_e32 v164, v164
	v_rcp_f32_e32 v165, v165
	v_rcp_f32_e32 v166, v166
	v_rcp_f32_e32 v167, v167
	v_pk_mul_f32 v[46:47], v[160:161], v[46:47]
	v_pk_mul_f32 v[48:49], v[162:163], v[48:49]
	v_pk_mul_f32 v[38:39], v[164:165], v[38:39]
	v_pk_mul_f32 v[40:41], v[166:167], v[40:41]
	v_cvt_pk_bf16_f32 v172, v46, v47
	v_cvt_pk_bf16_f32 v173, v48, v49
	v_cvt_pk_bf16_f32 v174, v38, v39
	v_cvt_pk_bf16_f32 v175, v40, v41
	flat_store_dwordx4 v[178:179], v[172:175]
	v_add_u32_e32 v176, 0xa0, v149
	v_mad_i64_i32 v[176:177], s[4:5], v176, s23, v[142:143]
	v_pk_mul_f32 v[160:161], v[30:31], s[100:101]
	v_pk_mul_f32 v[162:163], v[32:33], s[100:101]
	v_pk_mul_f32 v[164:165], v[22:23], s[100:101]
	v_pk_mul_f32 v[166:167], v[24:25], s[100:101]
	v_lshl_add_u64 v[176:177], v[176:177], 0, v[144:145]
	v_exp_f32_e32 v160, v160
	v_exp_f32_e32 v161, v161
	v_exp_f32_e32 v162, v162
	v_exp_f32_e32 v163, v163
	v_exp_f32_e32 v164, v164
	v_exp_f32_e32 v165, v165
	v_exp_f32_e32 v166, v166
	v_exp_f32_e32 v167, v167
	v_pk_mul_f32 v[30:31], v[30:31], v[26:27]
	v_pk_mul_f32 v[32:33], v[32:33], v[28:29]
	v_pk_mul_f32 v[22:23], v[22:23], v[18:19]
	v_pk_mul_f32 v[24:25], v[24:25], v[20:21]
	v_pk_add_f32 v[160:161], v[160:161], v[250:251]
	v_pk_add_f32 v[162:163], v[162:163], v[250:251]
	v_pk_add_f32 v[164:165], v[164:165], v[250:251]
	v_pk_add_f32 v[166:167], v[166:167], v[250:251]
	v_rcp_f32_e32 v160, v160
	v_rcp_f32_e32 v161, v161
	v_rcp_f32_e32 v162, v162
	v_rcp_f32_e32 v163, v163
	v_rcp_f32_e32 v164, v164
	v_rcp_f32_e32 v165, v165
	v_rcp_f32_e32 v166, v166
	v_rcp_f32_e32 v167, v167
	v_pk_mul_f32 v[30:31], v[160:161], v[30:31]
	v_pk_mul_f32 v[32:33], v[162:163], v[32:33]
	v_pk_mul_f32 v[22:23], v[164:165], v[22:23]
	v_pk_mul_f32 v[24:25], v[166:167], v[24:25]
	v_cvt_pk_bf16_f32 v168, v30, v31
	v_cvt_pk_bf16_f32 v169, v32, v33
	v_cvt_pk_bf16_f32 v170, v22, v23
	v_cvt_pk_bf16_f32 v171, v24, v25
	flat_store_dwordx4 v[176:177], v[168:171]
	v_add_u32_e32 v178, 0xb0, v149
	v_mad_i64_i32 v[178:179], s[4:5], v178, s23, v[142:143]
	v_pk_mul_f32 v[160:161], v[12:13], s[100:101]
	v_pk_mul_f32 v[162:163], v[14:15], s[100:101]
	v_pk_mul_f32 v[164:165], v[4:5], s[100:101]
	v_pk_mul_f32 v[166:167], v[6:7], s[100:101]
	v_lshl_add_u64 v[178:179], v[178:179], 0, v[144:145]
	v_exp_f32_e32 v160, v160
	v_exp_f32_e32 v161, v161
	v_exp_f32_e32 v162, v162
	v_exp_f32_e32 v163, v163
	v_exp_f32_e32 v164, v164
	v_exp_f32_e32 v165, v165
	v_exp_f32_e32 v166, v166
	v_exp_f32_e32 v167, v167
	v_pk_mul_f32 v[12:13], v[12:13], v[8:9]
	v_pk_mul_f32 v[14:15], v[14:15], v[10:11]
	v_pk_mul_f32 v[4:5], v[4:5], v[0:1]
	v_pk_mul_f32 v[6:7], v[6:7], v[2:3]
	v_pk_add_f32 v[160:161], v[160:161], v[250:251]
	v_pk_add_f32 v[162:163], v[162:163], v[250:251]
	v_pk_add_f32 v[164:165], v[164:165], v[250:251]
	v_pk_add_f32 v[166:167], v[166:167], v[250:251]
	v_rcp_f32_e32 v160, v160
	v_rcp_f32_e32 v161, v161
	v_rcp_f32_e32 v162, v162
	v_rcp_f32_e32 v163, v163
	v_rcp_f32_e32 v164, v164
	v_rcp_f32_e32 v165, v165
	v_rcp_f32_e32 v166, v166
	v_rcp_f32_e32 v167, v167
	v_pk_mul_f32 v[12:13], v[160:161], v[12:13]
	v_pk_mul_f32 v[14:15], v[162:163], v[14:15]
	v_pk_mul_f32 v[4:5], v[164:165], v[4:5]
	v_pk_mul_f32 v[6:7], v[166:167], v[6:7]
	v_cvt_pk_bf16_f32 v172, v12, v13
	v_cvt_pk_bf16_f32 v173, v14, v15
	v_cvt_pk_bf16_f32 v174, v4, v5
	v_cvt_pk_bf16_f32 v175, v6, v7
	flat_store_dwordx4 v[178:179], v[172:175]
	s_andn2_b64 vcc, exec, s[36:37]
	s_mov_b64 s[4:5], -1
	s_cbranch_vccnz .LBB0_215
	s_andn2_b64 vcc, exec, s[2:3]
	s_cbranch_vccnz .LBB0_214
	s_barrier
	s_branch .LBB0_214

.LBB0_1754:
	v_lshl_or_b32 v144, s58, 7, v147
	v_lshl_add_u32 v149, s40, 8, v17
	s_mov_b32 s100, 0xbfb8aa3b
	s_mov_b32 s101, 0xbfb8aa3b
	v_ashrrev_i32_e32 v145, 31, v144
	v_mov_b64_e32 v[142:143], s[12:13]
	s_movk_i32 s23, 0x2c00
	v_mov_b32_e32 v250, 1.0
	v_mov_b32_e32 v251, 1.0
	v_lshlrev_b64 v[144:145], 1, v[144:145]
	v_mad_i64_i32 v[176:177], s[4:5], v149, s23, v[142:143]
	v_pk_mul_f32 v[160:161], v[126:127], s[100:101]
	v_pk_mul_f32 v[162:163], v[128:129], s[100:101]
	v_pk_mul_f32 v[164:165], v[118:119], s[100:101]
	v_pk_mul_f32 v[166:167], v[120:121], s[100:101]
	v_lshl_add_u64 v[176:177], v[176:177], 0, v[144:145]
	v_exp_f32_e32 v160, v160
	v_exp_f32_e32 v161, v161
	v_exp_f32_e32 v162, v162
	v_exp_f32_e32 v163, v163
	v_exp_f32_e32 v164, v164
	v_exp_f32_e32 v165, v165
	v_exp_f32_e32 v166, v166
	v_exp_f32_e32 v167, v167
	v_pk_mul_f32 v[126:127], v[126:127], v[122:123]
	v_pk_mul_f32 v[128:129], v[128:129], v[124:125]
	v_pk_mul_f32 v[118:119], v[118:119], v[114:115]
	v_pk_mul_f32 v[120:121], v[120:121], v[116:117]
	v_pk_add_f32 v[160:161], v[160:161], v[250:251]
	v_pk_add_f32 v[162:163], v[162:163], v[250:251]
	v_pk_add_f32 v[164:165], v[164:165], v[250:251]
	v_pk_add_f32 v[166:167], v[166:167], v[250:251]
	v_rcp_f32_e32 v160, v160
	v_rcp_f32_e32 v161, v161
	v_rcp_f32_e32 v162, v162
	v_rcp_f32_e32 v163, v163
	v_rcp_f32_e32 v164, v164
	v_rcp_f32_e32 v165, v165
	v_rcp_f32_e32 v166, v166
	v_rcp_f32_e32 v167, v167
	v_pk_mul_f32 v[126:127], v[160:161], v[126:127]
	v_pk_mul_f32 v[128:129], v[162:163], v[128:129]
	v_pk_mul_f32 v[118:119], v[164:165], v[118:119]
	v_pk_mul_f32 v[120:121], v[166:167], v[120:121]
	v_cvt_pk_bf16_f32 v168, v126, v127
	v_cvt_pk_bf16_f32 v169, v128, v129
	v_cvt_pk_bf16_f32 v170, v118, v119
	v_cvt_pk_bf16_f32 v171, v120, v121
	flat_store_dwordx4 v[176:177], v[168:171]
	v_add_u32_e32 v178, 0x10, v149
	v_mad_i64_i32 v[178:179], s[4:5], v178, s23, v[142:143]
	v_pk_mul_f32 v[160:161], v[110:111], s[100:101]
	v_pk_mul_f32 v[162:163], v[112:113], s[100:101]
	v_pk_mul_f32 v[164:165], v[102:103], s[100:101]
	v_pk_mul_f32 v[166:167], v[104:105], s[100:101]
	v_lshl_add_u64 v[178:179], v[178:179], 0, v[144:145]
	v_exp_f32_e32 v160, v160
	v_exp_f32_e32 v161, v161
	v_exp_f32_e32 v162, v162
	v_exp_f32_e32 v163, v163
	v_exp_f32_e32 v164, v164
	v_exp_f32_e32 v165, v165
	v_exp_f32_e32 v166, v166
	v_exp_f32_e32 v167, v167
	v_pk_mul_f32 v[110:111], v[110:111], v[106:107]
	v_pk_mul_f32 v[112:113], v[112:113], v[108:109]
	v_pk_mul_f32 v[102:103], v[102:103], v[98:99]
	v_pk_mul_f32 v[104:105], v[104:105], v[100:101]
	v_pk_add_f32 v[160:161], v[160:161], v[250:251]
	v_pk_add_f32 v[162:163], v[162:163], v[250:251]
	v_pk_add_f32 v[164:165], v[164:165], v[250:251]
	v_pk_add_f32 v[166:167], v[166:167], v[250:251]
	v_rcp_f32_e32 v160, v160
	v_rcp_f32_e32 v161, v161
	v_rcp_f32_e32 v162, v162
	v_rcp_f32_e32 v163, v163
	v_rcp_f32_e32 v164, v164
	v_rcp_f32_e32 v165, v165
	v_rcp_f32_e32 v166, v166
	v_rcp_f32_e32 v167, v167
	v_pk_mul_f32 v[110:111], v[160:161], v[110:111]
	v_pk_mul_f32 v[112:113], v[162:163], v[112:113]
	v_pk_mul_f32 v[102:103], v[164:165], v[102:103]
	v_pk_mul_f32 v[104:105], v[166:167], v[104:105]
	v_cvt_pk_bf16_f32 v172, v110, v111
	v_cvt_pk_bf16_f32 v173, v112, v113
	v_cvt_pk_bf16_f32 v174, v102, v103
	v_cvt_pk_bf16_f32 v175, v104, v105
	flat_store_dwordx4 v[178:179], v[172:175]
	v_add_u32_e32 v176, 0x20, v149
	v_mad_i64_i32 v[176:177], s[4:5], v176, s23, v[142:143]
	v_pk_mul_f32 v[160:161], v[94:95], s[100:101]
	v_pk_mul_f32 v[162:163], v[96:97], s[100:101]
	v_pk_mul_f32 v[164:165], v[86:87], s[100:101]
	v_pk_mul_f32 v[166:167], v[88:89], s[100:101]
	v_lshl_add_u64 v[176:177], v[176:177], 0, v[144:145]
	v_exp_f32_e32 v160, v160
	v_exp_f32_e32 v161, v161
	v_exp_f32_e32 v162, v162
	v_exp_f32_e32 v163, v163
	v_exp_f32_e32 v164, v164
	v_exp_f32_e32 v165, v165
	v_exp_f32_e32 v166, v166
	v_exp_f32_e32 v167, v167
	v_pk_mul_f32 v[94:95], v[94:95], v[90:91]
	v_pk_mul_f32 v[96:97], v[96:97], v[92:93]
	v_pk_mul_f32 v[86:87], v[86:87], v[82:83]
	v_pk_mul_f32 v[88:89], v[88:89], v[84:85]
	v_pk_add_f32 v[160:161], v[160:161], v[250:251]
	v_pk_add_f32 v[162:163], v[162:163], v[250:251]
	v_pk_add_f32 v[164:165], v[164:165], v[250:251]
	v_pk_add_f32 v[166:167], v[166:167], v[250:251]
	v_rcp_f32_e32 v160, v160
	v_rcp_f32_e32 v161, v161
	v_rcp_f32_e32 v162, v162
	v_rcp_f32_e32 v163, v163
	v_rcp_f32_e32 v164, v164
	v_rcp_f32_e32 v165, v165
	v_rcp_f32_e32 v166, v166
	v_rcp_f32_e32 v167, v167
	v_pk_mul_f32 v[94:95], v[160:161], v[94:95]
	v_pk_mul_f32 v[96:97], v[162:163], v[96:97]
	v_pk_mul_f32 v[86:87], v[164:165], v[86:87]
	v_pk_mul_f32 v[88:89], v[166:167], v[88:89]
	v_cvt_pk_bf16_f32 v168, v94, v95
	v_cvt_pk_bf16_f32 v169, v96, v97
	v_cvt_pk_bf16_f32 v170, v86, v87
	v_cvt_pk_bf16_f32 v171, v88, v89
	flat_store_dwordx4 v[176:177], v[168:171]
	v_add_u32_e32 v178, 0x30, v149
	v_mad_i64_i32 v[178:179], s[4:5], v178, s23, v[142:143]
	v_pk_mul_f32 v[160:161], v[78:79], s[100:101]
	v_pk_mul_f32 v[162:163], v[80:81], s[100:101]
	v_pk_mul_f32 v[164:165], v[70:71], s[100:101]
	v_pk_mul_f32 v[166:167], v[72:73], s[100:101]
	v_lshl_add_u64 v[178:179], v[178:179], 0, v[144:145]
	v_exp_f32_e32 v160, v160
	v_exp_f32_e32 v161, v161
	v_exp_f32_e32 v162, v162
	v_exp_f32_e32 v163, v163
	v_exp_f32_e32 v164, v164
	v_exp_f32_e32 v165, v165
	v_exp_f32_e32 v166, v166
	v_exp_f32_e32 v167, v167
	v_pk_mul_f32 v[78:79], v[78:79], v[74:75]
	v_pk_mul_f32 v[80:81], v[80:81], v[76:77]
	v_pk_mul_f32 v[70:71], v[70:71], v[66:67]
	v_pk_mul_f32 v[72:73], v[72:73], v[68:69]
	v_pk_add_f32 v[160:161], v[160:161], v[250:251]
	v_pk_add_f32 v[162:163], v[162:163], v[250:251]
	v_pk_add_f32 v[164:165], v[164:165], v[250:251]
	v_pk_add_f32 v[166:167], v[166:167], v[250:251]
	v_rcp_f32_e32 v160, v160
	v_rcp_f32_e32 v161, v161
	v_rcp_f32_e32 v162, v162
	v_rcp_f32_e32 v163, v163
	v_rcp_f32_e32 v164, v164
	v_rcp_f32_e32 v165, v165
	v_rcp_f32_e32 v166, v166
	v_rcp_f32_e32 v167, v167
	v_pk_mul_f32 v[78:79], v[160:161], v[78:79]
	v_pk_mul_f32 v[80:81], v[162:163], v[80:81]
	v_pk_mul_f32 v[70:71], v[164:165], v[70:71]
	v_pk_mul_f32 v[72:73], v[166:167], v[72:73]
	v_cvt_pk_bf16_f32 v172, v78, v79
	v_cvt_pk_bf16_f32 v173, v80, v81
	v_cvt_pk_bf16_f32 v174, v70, v71
	v_cvt_pk_bf16_f32 v175, v72, v73
	flat_store_dwordx4 v[178:179], v[172:175]
	v_add_u32_e32 v176, 0x80, v149
	v_mad_i64_i32 v[176:177], s[4:5], v176, s23, v[142:143]
	v_pk_mul_f32 v[160:161], v[62:63], s[100:101]
	v_pk_mul_f32 v[162:163], v[64:65], s[100:101]
	v_pk_mul_f32 v[164:165], v[54:55], s[100:101]
	v_pk_mul_f32 v[166:167], v[56:57], s[100:101]
	v_lshl_add_u64 v[176:177], v[176:177], 0, v[144:145]
	v_exp_f32_e32 v160, v160
	v_exp_f32_e32 v161, v161
	v_exp_f32_e32 v162, v162
	v_exp_f32_e32 v163, v163
	v_exp_f32_e32 v164, v164
	v_exp_f32_e32 v165, v165
	v_exp_f32_e32 v166, v166
	v_exp_f32_e32 v167, v167
	v_pk_mul_f32 v[62:63], v[62:63], v[58:59]
	v_pk_mul_f32 v[64:65], v[64:65], v[60:61]
	v_pk_mul_f32 v[54:55], v[54:55], v[50:51]
	v_pk_mul_f32 v[56:57], v[56:57], v[52:53]
	v_pk_add_f32 v[160:161], v[160:161], v[250:251]
	v_pk_add_f32 v[162:163], v[162:163], v[250:251]
	v_pk_add_f32 v[164:165], v[164:165], v[250:251]
	v_pk_add_f32 v[166:167], v[166:167], v[250:251]
	v_rcp_f32_e32 v160, v160
	v_rcp_f32_e32 v161, v161
	v_rcp_f32_e32 v162, v162
	v_rcp_f32_e32 v163, v163
	v_rcp_f32_e32 v164, v164
	v_rcp_f32_e32 v165, v165
	v_rcp_f32_e32 v166, v166
	v_rcp_f32_e32 v167, v167
	v_pk_mul_f32 v[62:63], v[160:161], v[62:63]
	v_pk_mul_f32 v[64:65], v[162:163], v[64:65]
	v_pk_mul_f32 v[54:55], v[164:165], v[54:55]
	v_pk_mul_f32 v[56:57], v[166:167], v[56:57]
	v_cvt_pk_bf16_f32 v168, v62, v63
	v_cvt_pk_bf16_f32 v169, v64, v65
	v_cvt_pk_bf16_f32 v170, v54, v55
	v_cvt_pk_bf16_f32 v171, v56, v57
	flat_store_dwordx4 v[176:177], v[168:171]
	v_add_u32_e32 v178, 0x90, v149
	v_mad_i64_i32 v[178:179], s[4:5], v178, s23, v[142:143]
	v_pk_mul_f32 v[160:161], v[46:47], s[100:101]
	v_pk_mul_f32 v[162:163], v[48:49], s[100:101]
	v_pk_mul_f32 v[164:165], v[38:39], s[100:101]
	v_pk_mul_f32 v[166:167], v[40:41], s[100:101]
	v_lshl_add_u64 v[178:179], v[178:179], 0, v[144:145]
	v_exp_f32_e32 v160, v160
	v_exp_f32_e32 v161, v161
	v_exp_f32_e32 v162, v162
	v_exp_f32_e32 v163, v163
	v_exp_f32_e32 v164, v164
	v_exp_f32_e32 v165, v165
	v_exp_f32_e32 v166, v166
	v_exp_f32_e32 v167, v167
	v_pk_mul_f32 v[46:47], v[46:47], v[42:43]
	v_pk_mul_f32 v[48:49], v[48:49], v[44:45]
	v_pk_mul_f32 v[38:39], v[38:39], v[34:35]
	v_pk_mul_f32 v[40:41], v[40:41], v[36:37]
	v_pk_add_f32 v[160:161], v[160:161], v[250:251]
	v_pk_add_f32 v[162:163], v[162:163], v[250:251]
	v_pk_add_f32 v[164:165], v[164:165], v[250:251]
	v_pk_add_f32 v[166:167], v[166:167], v[250:251]
	v_rcp_f32_e32 v160, v160
	v_rcp_f32_e32 v161, v161
	v_rcp_f32_e32 v162, v162
	v_rcp_f32_e32 v163, v163
	v_rcp_f32_e32 v164, v164
	v_rcp_f32_e32 v165, v165
	v_rcp_f32_e32 v166, v166
	v_rcp_f32_e32 v167, v167
	v_pk_mul_f32 v[46:47], v[160:161], v[46:47]
	v_pk_mul_f32 v[48:49], v[162:163], v[48:49]
	v_pk_mul_f32 v[38:39], v[164:165], v[38:39]
	v_pk_mul_f32 v[40:41], v[166:167], v[40:41]
	v_cvt_pk_bf16_f32 v172, v46, v47
	v_cvt_pk_bf16_f32 v173, v48, v49
	v_cvt_pk_bf16_f32 v174, v38, v39
	v_cvt_pk_bf16_f32 v175, v40, v41
	flat_store_dwordx4 v[178:179], v[172:175]
	v_add_u32_e32 v176, 0xa0, v149
	v_mad_i64_i32 v[176:177], s[4:5], v176, s23, v[142:143]
	v_pk_mul_f32 v[160:161], v[30:31], s[100:101]
	v_pk_mul_f32 v[162:163], v[32:33], s[100:101]
	v_pk_mul_f32 v[164:165], v[22:23], s[100:101]
	v_pk_mul_f32 v[166:167], v[24:25], s[100:101]
	v_lshl_add_u64 v[176:177], v[176:177], 0, v[144:145]
	v_exp_f32_e32 v160, v160
	v_exp_f32_e32 v161, v161
	v_exp_f32_e32 v162, v162
	v_exp_f32_e32 v163, v163
	v_exp_f32_e32 v164, v164
	v_exp_f32_e32 v165, v165
	v_exp_f32_e32 v166, v166
	v_exp_f32_e32 v167, v167
	v_pk_mul_f32 v[30:31], v[30:31], v[26:27]
	v_pk_mul_f32 v[32:33], v[32:33], v[28:29]
	v_pk_mul_f32 v[22:23], v[22:23], v[18:19]
	v_pk_mul_f32 v[24:25], v[24:25], v[20:21]
	v_pk_add_f32 v[160:161], v[160:161], v[250:251]
	v_pk_add_f32 v[162:163], v[162:163], v[250:251]
	v_pk_add_f32 v[164:165], v[164:165], v[250:251]
	v_pk_add_f32 v[166:167], v[166:167], v[250:251]
	v_rcp_f32_e32 v160, v160
	v_rcp_f32_e32 v161, v161
	v_rcp_f32_e32 v162, v162
	v_rcp_f32_e32 v163, v163
	v_rcp_f32_e32 v164, v164
	v_rcp_f32_e32 v165, v165
	v_rcp_f32_e32 v166, v166
	v_rcp_f32_e32 v167, v167
	v_pk_mul_f32 v[30:31], v[160:161], v[30:31]
	v_pk_mul_f32 v[32:33], v[162:163], v[32:33]
	v_pk_mul_f32 v[22:23], v[164:165], v[22:23]
	v_pk_mul_f32 v[24:25], v[166:167], v[24:25]
	v_cvt_pk_bf16_f32 v168, v30, v31
	v_cvt_pk_bf16_f32 v169, v32, v33
	v_cvt_pk_bf16_f32 v170, v22, v23
	v_cvt_pk_bf16_f32 v171, v24, v25
	flat_store_dwordx4 v[176:177], v[168:171]
	v_add_u32_e32 v178, 0xb0, v149
	v_mad_i64_i32 v[178:179], s[4:5], v178, s23, v[142:143]
	v_pk_mul_f32 v[160:161], v[12:13], s[100:101]
	v_pk_mul_f32 v[162:163], v[14:15], s[100:101]
	v_pk_mul_f32 v[164:165], v[4:5], s[100:101]
	v_pk_mul_f32 v[166:167], v[6:7], s[100:101]
	v_lshl_add_u64 v[178:179], v[178:179], 0, v[144:145]
	v_exp_f32_e32 v160, v160
	v_exp_f32_e32 v161, v161
	v_exp_f32_e32 v162, v162
	v_exp_f32_e32 v163, v163
	v_exp_f32_e32 v164, v164
	v_exp_f32_e32 v165, v165
	v_exp_f32_e32 v166, v166
	v_exp_f32_e32 v167, v167
	v_pk_mul_f32 v[12:13], v[12:13], v[8:9]
	v_pk_mul_f32 v[14:15], v[14:15], v[10:11]
	v_pk_mul_f32 v[4:5], v[4:5], v[0:1]
	v_pk_mul_f32 v[6:7], v[6:7], v[2:3]
	v_pk_add_f32 v[160:161], v[160:161], v[250:251]
	v_pk_add_f32 v[162:163], v[162:163], v[250:251]
	v_pk_add_f32 v[164:165], v[164:165], v[250:251]
	v_pk_add_f32 v[166:167], v[166:167], v[250:251]
	v_rcp_f32_e32 v160, v160
	v_rcp_f32_e32 v161, v161
	v_rcp_f32_e32 v162, v162
	v_rcp_f32_e32 v163, v163
	v_rcp_f32_e32 v164, v164
	v_rcp_f32_e32 v165, v165
	v_rcp_f32_e32 v166, v166
	v_rcp_f32_e32 v167, v167
	v_pk_mul_f32 v[12:13], v[160:161], v[12:13]
	v_pk_mul_f32 v[14:15], v[162:163], v[14:15]
	v_pk_mul_f32 v[4:5], v[164:165], v[4:5]
	v_pk_mul_f32 v[6:7], v[166:167], v[6:7]
	v_cvt_pk_bf16_f32 v172, v12, v13
	v_cvt_pk_bf16_f32 v173, v14, v15
	v_cvt_pk_bf16_f32 v174, v4, v5
	v_cvt_pk_bf16_f32 v175, v6, v7
	flat_store_dwordx4 v[178:179], v[172:175]
	s_andn2_b64 vcc, exec, s[36:37]
	s_mov_b64 s[4:5], -1
	s_cbranch_vccnz .LBB0_1747
	s_andn2_b64 vcc, exec, s[2:3]
	s_cbranch_vccnz .LBB0_1746
	s_barrier
	s_branch .LBB0_1746
